# attention K tiles staged as whole 128-byte rows (8 lanes per row, XOR-swizzled LDS image) instead of one 16-byte chunk per row per lane; scalar-base DMA addressing in attention
# speedup vs baseline: 1.0283x; 1.0089x over previous
; __device__ __forceinline__ void attn_unit(const int b, const int h, const int qb, const bf16_t* Q, const bf16_t* K, const bf16_t* V, bf16_t* O, ATT_LAS char* shm, const float lam) {
;     const int tid = threadIdx.x, lane = tid & 63, r32 = lane & 31, hi = lane >> 5; const int wid = __builtin_amdgcn_readfirstlane(tid >> 6), sub = wid >> 2, w4 = wid & 3;
;     const long rowbase = (long)b * SEQ; const int q0 = qb * QB2;
;     const bf16_t* Qw = Q + (rowbase + q0 + w4 * QBLK) * PITCH + h * 128 + sub * 64;
;     const bf16_t* Kh = K + rowbase * PITCH + h * 128; const bf16_t* Vh = V + rowbase * PITCH + h * 128;
;     const unsigned lds0 = (unsigned)(uintptr_t)shm;
;     const bf16_t* ksrc = Kh + (long)lane * PITCH + wid * 8;
;     const bf16_t* vsrc = Vh + (long)(16 * (wid & 3) + (lane >> 2)) * PITCH + (wid >> 2) * 32 + (lane & 3) * 8;
;     const unsigned pdst = lds0 + wid * 1024;
;     ...
;     const lds_cptr kp0 = (lds_cptr)shm + sub * OFF_K1 + hi * 1024 + r32 * 16;
;     const lds_cptr vp0 = (lds_cptr)shm + OFF_V + ((lane >> 4) & 1) * 32 + (lane & 3) * 8 + (4 * hi + ((lane & 15) >> 2)) * 64;
.LBB0_463:
	s_andn2_b64 vcc, exec, s[0:1]
	s_cbranch_vccnz .LBB0_479
	v_and_b32_e32 v151, 31, v164
	v_lshrrev_b32_e32 v3, 5, v238
	v_lshlrev_b32_e32 v2, 7, v164
	v_lshlrev_b32_e32 v6, 1, v238
	v_and_b32_e32 v152, 0x1e00, v2
	v_and_b32_e32 v2, 24, v132
	v_lshlrev_b32_e32 v153, 10, v3
	v_lshlrev_b32_e32 v4, 4, v151
	v_and_b32_e32 v6, 32, v6
	v_lshlrev_b32_e32 v8, 4, v164
	v_add3_u32 v6, 0, v6, v2
	v_lshlrev_b32_e32 v7, 8, v3
	v_add3_u32 v154, 0, v153, v4
	v_lshlrev_b32_e32 v4, 9, v151
	v_and_b32_e32 v8, 0xc0, v8
	v_lshl_or_b32 v4, v3, 3, v4
	v_add3_u32 v156, v6, v7, v8
	v_lshlrev_b32_e32 v6, 4, v3
	v_lshlrev_b32_e32 v7, 2, v150
	s_movk_i32 s3, 0x100
	v_lshlrev_b32_e32 v3, 2, v3
	v_and_or_b32 v150, v7, s3, v6
	v_or_b32_e32 v6, v143, v3
	v_lshlrev_b32_e32 v174, 2, v6
	v_or_b32_e32 v6, 1, v3
	v_or_b32_e32 v7, v143, v6
	v_lshlrev_b32_e32 v176, 8, v6
	v_or_b32_e32 v6, 2, v3
	v_lshlrev_b32_e32 v175, 2, v7
	v_or_b32_e32 v7, v143, v6
	v_lshlrev_b32_e32 v178, 8, v6
	v_or_b32_e32 v6, 3, v3
	v_lshlrev_b32_e32 v177, 2, v7
	v_or_b32_e32 v7, v143, v6
	v_lshlrev_b32_e32 v180, 8, v6
	v_or_b32_e32 v6, 8, v3
	v_lshlrev_b32_e32 v179, 2, v7
	v_or_b32_e32 v7, v143, v6
	v_lshlrev_b32_e32 v182, 8, v6
	v_or_b32_e32 v6, 9, v3
	v_lshlrev_b32_e32 v181, 2, v7
	v_or_b32_e32 v7, v143, v6
	v_lshlrev_b32_e32 v184, 8, v6
	v_or_b32_e32 v6, 10, v3
	v_lshlrev_b32_e32 v183, 2, v7
	v_or_b32_e32 v7, v143, v6
	v_lshlrev_b32_e32 v186, 8, v6
	v_or_b32_e32 v6, 11, v3
	v_lshlrev_b32_e32 v185, 2, v7
	v_or_b32_e32 v7, v143, v6
	v_lshlrev_b32_e32 v188, 8, v6
	v_or_b32_e32 v6, 16, v3
	v_lshlrev_b32_e32 v187, 2, v7
	v_or_b32_e32 v7, v143, v6
	v_lshlrev_b32_e32 v190, 8, v6
	v_or_b32_e32 v6, 17, v3
	v_lshlrev_b32_e32 v189, 2, v7
	v_or_b32_e32 v7, v143, v6
	v_lshlrev_b32_e32 v192, 8, v6
	v_or_b32_e32 v6, 18, v3
	s_ashr_i32 s8, s76, 5
	v_lshlrev_b32_e32 v191, 2, v7
	v_or_b32_e32 v7, v143, v6
	v_lshlrev_b32_e32 v194, 8, v6
	v_or_b32_e32 v6, 19, v3
	s_and_b32 s6, s76, 31
	s_ashr_i32 s9, s8, 31
	v_lshlrev_b32_e32 v193, 2, v7
	v_or_b32_e32 v7, v143, v6
	v_lshlrev_b32_e32 v196, 8, v6
	v_or_b32_e32 v6, 24, v3
	s_xor_b32 s7, s6, 31
	s_lshl_b64 s[0:1], s[8:9], 21
	s_lshl_b64 s[18:19], s[8:9], 22
	v_lshlrev_b32_e32 v195, 2, v7
	v_or_b32_e32 v7, v143, v6
	v_lshlrev_b32_e32 v198, 8, v6
	v_or_b32_e32 v6, 25, v3
	s_add_u32 s16, s89, s18
	v_lshrrev_b32_e32 v5, 4, v238
	v_lshlrev_b32_e32 v197, 2, v7
	v_or_b32_e32 v7, v143, v6
	v_lshlrev_b32_e32 v200, 8, v6
	v_or_b32_e32 v6, 26, v3
	v_or_b32_e32 v3, 27, v3
	s_addc_u32 s17, s90, s19
	v_lshlrev_b32_e32 v199, 2, v7
	v_or_b32_e32 v7, v143, v6
	v_lshlrev_b32_e32 v202, 8, v6
	v_or_b32_e32 v6, v143, v3
	v_lshlrev_b32_e32 v204, 8, v3
	v_or_b32_e32 v3, 4, v5
	s_add_u32 s8, s87, s18
	v_lshlrev_b32_e32 v206, 8, v3
	v_lshlrev_b32_e32 v10, 9, v3
	v_or_b32_e32 v3, 8, v5
	s_addc_u32 s9, s88, s19
	v_lshlrev_b32_e32 v207, 8, v3
	v_lshlrev_b32_e32 v12, 9, v3
	v_or_b32_e32 v3, 12, v5
	v_lshlrev_b32_e32 v208, 8, v3
	v_lshlrev_b32_e32 v14, 9, v3
	v_or_b32_e32 v3, 16, v5
	s_add_u32 s18, s58, s18
	v_lshrrev_b32_e32 v26, 6, v164
	v_and_b32_e32 v26, 1, v26
	v_lshlrev_b32_e32 v26, 2, v26
	v_lshrrev_b32_e32 v27, 4, v238
	v_or_b32_e32 v26, v26, v27
	v_and_b32_e32 v27, 7, v238
	v_xor_b32_e32 v26, v26, v27
	v_lshlrev_b32_e32 v26, 4, v26
	v_lshrrev_b32_e32 v27, 3, v238
	v_lshl_or_b32 v0, v27, 10, v26
	v_mov_b32_e32 v1, 0
	v_lshlrev_b32_e32 v209, 8, v3
	v_lshlrev_b32_e32 v16, 9, v3
	v_or_b32_e32 v3, 20, v5
	s_addc_u32 s19, s59, s19
	v_lshl_add_u64 v[114:115], s[16:17], 0, v[0:1]
	v_lshlrev_b32_e32 v210, 8, v3
	v_lshlrev_b32_e32 v18, 9, v3
	v_or_b32_e32 v3, 24, v5
	v_lshl_add_u64 v[24:25], s[18:19], 0, v[0:1]
	v_and_b32_e32 v0, 3, v164
	v_lshlrev_b32_e32 v211, 8, v3
	v_lshlrev_b32_e32 v20, 9, v3
	v_or_b32_e32 v3, 28, v5
	s_mov_b64 s[20:21], 0xc820000
	v_lshlrev_b32_e32 v0, 4, v0
	v_lshlrev_b32_e32 v203, 2, v6
	v_and_b32_e32 v6, 0x78, v132
	v_lshlrev_b32_e32 v8, 9, v5
	v_lshlrev_b32_e32 v22, 9, v3
	v_lshl_add_u64 v[116:117], v[24:25], 0, s[20:21]
	v_lshl_add_u64 v[24:25], s[18:19], 0, v[0:1]
	s_mov_b64 s[18:19], 0xe820000
	s_mov_b32 s17, 0
	v_lshl_add_u32 v155, v238, 2, 0
	v_or_b32_e32 v157, 64, v150
	v_or_b32_e32 v254, 0x44, v150
	v_or_b32_e32 v215, 0x48, v150
	v_or_b32_e32 v165, 0x4c, v150
	v_or_b32_e32 v170, 0x60, v150
	v_or_b32_e32 v171, 0x64, v150
	v_or_b32_e32 v172, 0x68, v150
	v_or_b32_e32 v173, 0x6c, v150
	v_lshlrev_b32_e32 v201, 2, v7
	v_lshlrev_b32_e32 v205, 8, v5
	v_lshlrev_b32_e32 v212, 8, v3
	v_lshl_add_u64 v[118:119], v[24:25], 0, s[18:19]
	v_lshlrev_b32_e32 v120, 1, v2
	s_mov_b64 s[18:19], 0x80
	s_mov_b64 s[20:21], 0x10000
	s_mov_b64 s[22:23], 0x10080
	v_lshlrev_b32_e32 v213, 1, v4
	v_mov_b32_e32 v214, 0x358637bd
	v_lshlrev_b32_e32 v122, 1, v6
	v_lshlrev_b32_e32 v124, 1, v8
	v_lshlrev_b32_e32 v126, 1, v10
	v_lshlrev_b32_e32 v128, 1, v12
	v_lshlrev_b32_e32 v130, 1, v14
	v_lshlrev_b32_e32 v132, 1, v16
	v_lshlrev_b32_e32 v134, 1, v18
	v_lshlrev_b32_e32 v136, 1, v20
	v_lshlrev_b32_e32 v138, 1, v22
	s_mov_b64 s[24:25], 0x100
	s_mov_b32 s34, 0
	s_branch .LBB0_466

; #define ATT_WAIT_BAR(N) asm volatile("s_waitcnt vmcnt(" #N ") lgkmcnt(0)\n\ts_barrier" ::: "memory")
; #define DMA_T(t, s) do { const long go_ = (long)(t) * KVBLK * PITCH; const unsigned sd_ = (unsigned)__builtin_amdgcn_readfirstlane(pdst + (s) * SLOTB); \
;         glds16(ksrc + go_, sd_); glds16(ksrc + go_ + 64, sd_ + OFF_K1); glds16(vsrc + go_, sd_ + OFF_V); glds16(vsrc + go_ + 64, sd_ + OFF_V + 8192); } while (0)
; __device__ __forceinline__ void attn_unit(const int b, const int h, const int qb, const bf16_t* Q, const bf16_t* K, const bf16_t* V, bf16_t* O, ATT_LAS char* shm, const float lam) {
;     const int tid = threadIdx.x, lane = tid & 63, r32 = lane & 31, hi = lane >> 5; const int wid = __builtin_amdgcn_readfirstlane(tid >> 6), sub = wid >> 2, w4 = wid & 3;
;     const long rowbase = (long)b * SEQ; const int q0 = qb * QB2;
;     const bf16_t* Qw = Q + (rowbase + q0 + w4 * QBLK) * PITCH + h * 128 + sub * 64;
;     const bf16_t* Kh = K + rowbase * PITCH + h * 128; const bf16_t* Vh = V + rowbase * PITCH + h * 128;
;     const unsigned lds0 = (unsigned)(uintptr_t)shm;
;     const bf16_t* ksrc = Kh + (long)lane * PITCH + wid * 8;
;     const bf16_t* vsrc = Vh + (long)(16 * (wid & 3) + (lane >> 2)) * PITCH + (wid >> 2) * 32 + (lane & 3) * 8;
;     const unsigned pdst = lds0 + wid * 1024;
;     ...
;     const lds_cptr kp0 = (lds_cptr)shm + sub * OFF_K1 + hi * 1024 + r32 * 16;
;     const lds_cptr vp0 = (lds_cptr)shm + OFF_V + ((lane >> 4) & 1) * 32 + (lane & 3) * 8 + (4 * hi + ((lane & 15) >> 2)) * 64;
;     const int NT = (q0 + QB2) / KVBLK;
;     const int mylast = q0 / KVBLK + (w4 >> 1);
;     DMA_T(0, 0); DMA_T(1, 1);
;     bf16x8 qr[4];
; #pragma unroll
;     for (int d0 = 0; d0 < 4; ++d0) qr[d0] = *reinterpret_cast<const bf16x8*>(&Qw[(long)r32 * PITCH + d0 * 16 + hi * 8]);
;     asm volatile("" : "+v"(qr[0]), "+v"(qr[1]), "+v"(qr[2]), "+v"(qr[3]));
;     f32x16 o[4]; o[0] = f32x16{}; o[1] = f32x16{}; o[2] = f32x16{}; o[3] = f32x16{};
;     float l_reg = 0.f;
;     int slot = 0, slot2 = 2;
;     for (int t = 0; t < NT; ++t) {
;         if (t + 1 < NT) { ATT_WAIT_BAR(4); } else { ATT_WAIT_BAR(0); }
;         if (t + 2 < NT) DMA_T(t + 2, slot2);
.LBB0_466:
	s_bitcmp0_b32 s34, 0
	v_readfirstlane_b32 s3, v164
	s_cselect_b32 s44, s6, s7
	s_bfe_u32 s31, s3, 0x20006
	s_lshl_b32 s30, s31, 14
	s_lshl_b32 s16, s44, 16
	s_or_b32 s16, s30, s16
	s_or_b32 s26, s0, s16
	s_mov_b32 s27, s1
	s_lshr_b32 s45, s3, 6
	s_lshr_b32 s39, s3, 8
	s_lshl_b32 s46, s44, 7
	s_lshl_b64 s[26:27], s[26:27], 1
	s_add_u32 s36, s85, s26
	s_addc_u32 s37, s86, s27
	s_lshl_b32 s35, s34, 7
	s_lshl_b32 s16, s34, 8
	s_add_u32 s38, s36, s16
	s_addc_u32 s41, s37, 0
	s_lshl_b32 s36, s39, 6
	s_lshl_b32 s40, s39, 7
	s_add_u32 s40, s38, s40
	s_addc_u32 s41, s41, 0
	s_add_u32 s42, s8, s16
	s_addc_u32 s43, s9, 0
	s_lshl_b32 s38, s31, 13
	v_or_b32_e32 v0, s38, v152
	v_lshl_add_u64 v[2:3], v[114:115], 0, s[16:17]
	s_lshl_b32 s16, s45, 13
	v_lshlrev_b32_e32 v0, 1, v0
	s_lshl_b32 s31, s45, 10
	s_mov_b32 s37, s17
	v_lshl_add_u64 v[2:3], v[2:3], 0, s[16:17]
	v_lshl_add_u64 v[4:5], s[42:43], 0, v[0:1]
	s_add_i32 s31, s31, 0
	s_mov_b32 s16, m0
	s_mov_b32 m0, s31
	s_nop 0
	global_load_lds_dwordx4 v[2:3], off
	s_mov_b32 m0, s16
	v_lshl_add_u64 v[4:5], v[4:5], 0, s[36:37]
	v_mov_b32_e32 v121, v1
	v_lshl_add_u64 v[6:7], v[2:3], 0, s[18:19]
	s_add_i32 s16, s31, 0x2000
	s_mov_b32 s42, m0
	s_mov_b32 m0, s16
	s_nop 0
	global_load_lds_dwordx4 v[6:7], off
	s_mov_b32 m0, s42
	v_lshl_add_u64 v[4:5], v[4:5], 0, v[120:121]
	s_add_i32 s16, s31, 0x4000
	s_mov_b32 s42, m0
	s_mov_b32 m0, s16
	s_nop 0
	global_load_lds_dwordx4 v[4:5], off
	s_mov_b32 m0, s42
	v_lshl_add_u64 v[6:7], v[4:5], 0, s[18:19]
	s_add_i32 s16, s31, 0x6000
	s_mov_b32 s42, m0
	s_mov_b32 m0, s16
	s_nop 0
	global_load_lds_dwordx4 v[6:7], off
	s_mov_b32 m0, s42
	s_add_i32 s16, s31, 0x8000
	v_lshl_add_u64 v[6:7], v[2:3], 0, s[20:21]
	s_mov_b32 s42, m0
	s_mov_b32 m0, s16
	s_nop 0
	global_load_lds_dwordx4 v[6:7], off
	s_mov_b32 m0, s42
	v_lshl_add_u64 v[2:3], v[2:3], 0, s[22:23]
	s_add_i32 s16, s31, 0xa000
	s_mov_b32 s42, m0
	s_mov_b32 m0, s16
	s_nop 0
	global_load_lds_dwordx4 v[2:3], off
	s_mov_b32 m0, s42
	v_lshl_add_u64 v[2:3], v[4:5], 0, s[20:21]
	s_add_i32 s16, s31, 0xc000
	s_mov_b32 s42, m0
	s_mov_b32 m0, s16
	s_nop 0
	global_load_lds_dwordx4 v[2:3], off
	s_mov_b32 m0, s42
	v_lshl_add_u64 v[2:3], v[4:5], 0, s[22:23]
	s_add_i32 s16, s31, 0xe000
	s_mov_b32 s42, m0
	s_mov_b32 m0, s16
	s_nop 0
	global_load_lds_dwordx4 v[2:3], off
	s_mov_b32 m0, s42
	global_load_dwordx4 v[98:101], v213, s[40:41] offset:96
	global_load_dwordx4 v[102:105], v213, s[40:41] offset:64
	global_load_dwordx4 v[106:109], v213, s[40:41] offset:32
	global_load_dwordx4 v[110:113], v213, s[40:41]
	v_mov_b32_e32 v14, v1
	v_mov_b32_e32 v15, v1
	v_mov_b32_e32 v2, v1
	v_mov_b32_e32 v3, v1
	v_mov_b32_e32 v4, v1
	v_mov_b32_e32 v5, v1
	v_mov_b32_e32 v6, v1
	v_mov_b32_e32 v7, v1
	v_mov_b32_e32 v8, v1
	v_mov_b32_e32 v9, v1
	v_mov_b32_e32 v10, v1
	v_mov_b32_e32 v11, v1
	v_mov_b32_e32 v12, v1
	v_mov_b32_e32 v13, v1
	s_addk_i32 s46, 0x80
	s_bfe_u32 s16, s45, 0x10001
	s_lshl_b32 s42, s44, 1
	s_lshr_b32 s44, s3, 2
	v_lshl_add_u64 v[16:17], s[36:37], 0, v[0:1]
	v_mov_b32_e32 v0, v1
	v_mov_b64_e32 v[64:65], v[14:15]
	v_mov_b64_e32 v[48:49], v[14:15]
	v_mov_b64_e32 v[32:33], v[14:15]
	s_lshr_b32 s43, s46, 6
	s_or_b32 s42, s16, s42
	s_lshr_b32 s16, s3, 6
	s_lshl_b32 s16, s16, 13
	v_lshl_add_u64 v[142:143], v[118:119], 0, v[16:17]
	v_mov_b64_e32 v[62:63], v[12:13]
	v_mov_b64_e32 v[60:61], v[10:11]
	v_mov_b64_e32 v[58:59], v[8:9]
	v_mov_b64_e32 v[56:57], v[6:7]
	v_mov_b64_e32 v[54:55], v[4:5]
	v_mov_b64_e32 v[52:53], v[2:3]
	v_mov_b64_e32 v[50:51], v[0:1]
	v_mov_b64_e32 v[46:47], v[12:13]
	v_mov_b64_e32 v[44:45], v[10:11]
	v_mov_b64_e32 v[42:43], v[8:9]
	v_mov_b64_e32 v[40:41], v[6:7]
	v_mov_b64_e32 v[38:39], v[4:5]
	v_mov_b64_e32 v[36:37], v[2:3]
	v_mov_b64_e32 v[34:35], v[0:1]
	v_mov_b64_e32 v[30:31], v[12:13]
	v_mov_b64_e32 v[28:29], v[10:11]
	v_mov_b64_e32 v[26:27], v[8:9]
	v_mov_b64_e32 v[24:25], v[6:7]
	v_mov_b64_e32 v[22:23], v[4:5]
	v_mov_b64_e32 v[20:21], v[2:3]
	v_mov_b64_e32 v[18:19], v[0:1]
	v_mov_b64_e32 v[16:17], v[14:15]
	v_mov_b32_e32 v121, 0
	s_mov_b32 s40, 0
	s_mov_b32 s41, 2
	v_lshl_add_u32 v123, s39, 13, v154
	s_add_i32 s44, s43, -2
	s_add_i32 s45, s43, -1
	v_lshl_add_u64 v[140:141], v[116:117], 0, s[16:17]
	v_mov_b64_e32 v[14:15], v[12:13]
	v_mov_b64_e32 v[12:13], v[10:11]
	v_mov_b64_e32 v[10:11], v[8:9]
	v_mov_b64_e32 v[8:9], v[6:7]
	v_mov_b64_e32 v[6:7], v[4:5]
	v_mov_b64_e32 v[4:5], v[2:3]
	v_mov_b64_e32 v[2:3], v[0:1]
	s_mov_b32 s16, 0
	s_waitcnt vmcnt(0)
	v_and_b32_e32 v0, 63, v164
	v_and_b32_e32 v125, 31, v0
	v_lshlrev_b32_e32 v123, 7, v125
	v_lshl_add_u32 v123, s39, 13, v123
	v_lshrrev_b32_e32 v125, 5, v0
	v_bfe_u32 v162, v0, 1, 1
	v_xor_b32_e32 v125, v125, v162
	v_lshl_add_u32 v123, v125, 4, v123
	v_bfe_u32 v125, v0, 2, 2
	v_lshl_add_u32 v123, v125, 5, v123
	s_cmp_lt_u32 s43, 3
	s_cbranch_scc1 .Latt_nok2
	s_add_i32 s46, s31, 0x10000
	s_mov_b32 m0, s46
	v_lshl_add_u64 v[162:163], v[140:141], 0, s[18:19]
	global_load_lds_dwordx4 v[140:141], off
	s_add_i32 m0, s46, 0x2000
	s_nop 0
	global_load_lds_dwordx4 v[162:163], off
	v_lshl_add_u64 v[140:141], v[140:141], 0, s[20:21]
; #define ATT_LAS __attribute__((address_space(3)))
; __device__ __forceinline__ unsigned cvtpk_s(float lo, float hi) { f32x2_t v = {lo, hi}; bf16x2_t b = __builtin_convertvector(v, bf16x2_t); return __builtin_bit_cast(unsigned, b); }
; #define ATT_WAIT_BAR(N) asm volatile("s_waitcnt vmcnt(" #N ") lgkmcnt(0)\n\ts_barrier" ::: "memory")
; #define DMA_T(t, s) do { const long go_ = (long)(t) * KVBLK * PITCH; const unsigned sd_ = (unsigned)__builtin_amdgcn_readfirstlane(pdst + (s) * SLOTB); \
;         glds16(ksrc + go_, sd_); glds16(ksrc + go_ + 64, sd_ + OFF_K1); glds16(vsrc + go_, sd_ + OFF_V); glds16(vsrc + go_ + 64, sd_ + OFF_V + 8192); } while (0)
; #define ATT_SBAR() __builtin_amdgcn_sched_barrier(0)
; __device__ __forceinline__ void attn_unit(const int b, const int h, const int qb, const bf16_t* Q, const bf16_t* K, const bf16_t* V, bf16_t* O, ATT_LAS char* shm, const float lam) {
;     ...
;     for (int t = 0; t < NT; ++t) {
;         if (t + 1 < NT) { ATT_WAIT_BAR(4); } else { ATT_WAIT_BAR(0); }
;         if (t + 2 < NT) DMA_T(t + 2, slot2);
;         if (t <= mylast) {
;             const lds_cptr kp = kp0 + slot * SLOTB; const lds_cptr vp = vp0 + slot * SLOTB;
;     ...
;             bf16x8 kf[8]; s16x4 va[8], vb[8];
; #pragma unroll
;             for (int d0 = 0; d0 < 4; ++d0) { kf[2 * d0] = *(const ATT_LAS bf16x8*)(kp + d0 * 2048); kf[2 * d0 + 1] = *(const ATT_LAS bf16x8*)(kp + d0 * 2048 + 512); }
;             ATT_VLOAD(va, 0);
;             ATT_SBAR();
;             f32x16 p0 = f32x16{}, p1 = f32x16{};
; #pragma unroll
;             for (int d0 = 0; d0 < 4; ++d0) { p0 = __builtin_amdgcn_mfma_f32_32x32x16_bf16(kf[2 * d0], qr[d0], p0, 0, 0, 0); p1 = __builtin_amdgcn_mfma_f32_32x32x16_bf16(kf[2 * d0 + 1], qr[d0], p1, 0, 0, 0); }
;             ATT_SBAR();
;             ATT_VLOAD(vb, 1);
;             ATT_SBAR();
; #pragma unroll
;             for (int r = 0; r < 16; ++r) { p0[r] = __builtin_amdgcn_exp2f(p0[r]); p1[r] = __builtin_amdgcn_exp2f(p1[r]); }
;             u32x4 pw[4];
; #pragma unroll
;             for (int j = 0; j < 4; ++j) { pw[0][j] = cvtpk_s(p0[2 * j], p0[2 * j + 1]); pw[1][j] = cvtpk_s(p0[8 + 2 * j], p0[9 + 2 * j]); pw[2][j] = cvtpk_s(p1[2 * j], p1[2 * j + 1]); pw[3][j] = cvtpk_s(p1[8 + 2 * j], p1[9 + 2 * j]); }
.Latt_nok2:
	s_nop 1
	v_readfirstlane_b32 s100, v140
	v_readfirstlane_b32 s101, v141
	s_nop 1
	s_bfe_u32 s36, s3, 0x10006
	s_lshl_b32 s36, s36, 6
	s_sub_u32 s100, s100, s36
	s_subb_u32 s101, s101, 0
	v_subrev_u32_e32 v140, s100, v140
	v_subrev_u32_e32 v142, s100, v142
	s_and_b32 s98, s42, 1
	s_barrier
	v_add_u32_e32 v0, 0, v123
	v_xor_b32_e32 v162, 32, v0
	v_xor_b32_e32 v163, 64, v0
	v_xor_b32_e32 v141, 0x60, v0
	ds_read_b128 v[232:235], v0
	ds_read_b128 v[236:239], v162
	ds_read_b128 v[240:243], v163
	ds_read_b128 v[244:247], v141
	s_waitcnt lgkmcnt(3)
	v_mfma_f32_32x32x16_bf16 v[66:81], v[232:235], v[110:113], 0
	ds_read_b128 v[232:235], v0 offset:4096
	s_waitcnt lgkmcnt(3)
	v_mfma_f32_32x32x16_bf16 v[66:81], v[236:239], v[106:109], v[66:81]
	ds_read_b128 v[236:239], v162 offset:4096
	s_waitcnt lgkmcnt(3)
	v_mfma_f32_32x32x16_bf16 v[66:81], v[240:243], v[102:105], v[66:81]
	ds_read_b128 v[240:243], v163 offset:4096
	s_waitcnt lgkmcnt(3)
	v_mfma_f32_32x32x16_bf16 v[66:81], v[244:247], v[98:101], v[66:81]
	ds_read_b128 v[244:247], v141 offset:4096
	s_waitcnt lgkmcnt(3)
	v_mfma_f32_32x32x16_bf16 v[82:97], v[232:235], v[110:113], 0
	s_waitcnt lgkmcnt(2)
	v_mfma_f32_32x32x16_bf16 v[82:97], v[236:239], v[106:109], v[82:97]
	s_waitcnt lgkmcnt(1)
	v_mfma_f32_32x32x16_bf16 v[82:97], v[240:243], v[102:105], v[82:97]
	s_waitcnt lgkmcnt(0)
	v_mfma_f32_32x32x16_bf16 v[82:97], v[244:247], v[98:101], v[82:97]
	s_nop 15
	v_exp_f32_e32 v66, v66
	v_exp_f32_e32 v67, v67
	v_exp_f32_e32 v68, v68
	v_exp_f32_e32 v69, v69
	v_exp_f32_e32 v70, v70
	v_exp_f32_e32 v71, v71
	v_exp_f32_e32 v72, v72
	v_exp_f32_e32 v73, v73
	v_exp_f32_e32 v74, v74
	v_exp_f32_e32 v75, v75
	v_exp_f32_e32 v76, v76
	v_exp_f32_e32 v77, v77
	v_exp_f32_e32 v78, v78
	v_exp_f32_e32 v79, v79
	v_exp_f32_e32 v80, v80
	v_exp_f32_e32 v81, v81
	v_exp_f32_e32 v82, v82
	v_exp_f32_e32 v83, v83
	v_exp_f32_e32 v84, v84
	v_exp_f32_e32 v85, v85
	v_exp_f32_e32 v86, v86
	v_exp_f32_e32 v87, v87
	v_exp_f32_e32 v88, v88
	v_exp_f32_e32 v89, v89
	v_exp_f32_e32 v90, v90
	v_exp_f32_e32 v91, v91
	v_exp_f32_e32 v92, v92
	v_exp_f32_e32 v93, v93
	v_exp_f32_e32 v94, v94
	v_exp_f32_e32 v95, v95
	v_exp_f32_e32 v96, v96
	v_exp_f32_e32 v97, v97
	v_add_f32_e32 v252, v66, v67
	v_add_f32_e32 v252, v252, v68
	v_add_f32_e32 v252, v252, v69
	v_add_f32_e32 v252, v252, v70
	v_add_f32_e32 v252, v252, v71
	v_add_f32_e32 v252, v252, v72
	v_add_f32_e32 v252, v252, v73
	v_add_f32_e32 v252, v252, v74
	v_add_f32_e32 v252, v252, v75
	v_add_f32_e32 v252, v252, v76
	v_add_f32_e32 v252, v252, v77
	v_add_f32_e32 v252, v252, v78
	v_add_f32_e32 v252, v252, v79
	v_add_f32_e32 v252, v252, v80
	v_add_f32_e32 v252, v252, v81
	v_add_f32_e32 v253, v82, v83
	v_add_f32_e32 v253, v253, v84
	v_add_f32_e32 v253, v253, v85
	v_add_f32_e32 v253, v253, v86
	v_add_f32_e32 v253, v253, v87
	v_add_f32_e32 v253, v253, v88
	v_add_f32_e32 v253, v253, v89
	v_add_f32_e32 v253, v253, v90
	v_add_f32_e32 v253, v253, v91
	v_add_f32_e32 v253, v253, v92
	v_add_f32_e32 v253, v253, v93
	v_add_f32_e32 v253, v253, v94
	v_add_f32_e32 v253, v253, v95
	v_add_f32_e32 v253, v253, v96
	v_add_f32_e32 v253, v253, v97
	s_cmp_lt_u32 s43, 3
	s_cbranch_scc1 .Latt_tail
.Latt_top:
	s_add_i32 s36, s16, 3
	s_cmp_lt_u32 s36, s43
	s_cselect_b32 s99, 1, 0
	s_waitcnt vmcnt(4)
	s_barrier
	s_add_i32 s36, s40, 1
	s_cmp_lg_u32 s40, 2
	s_cselect_b32 s36, s36, 0
	s_lshl_b32 s36, s36, 15
	v_add_u32_e32 v0, s36, v123
	v_xor_b32_e32 v162, 32, v0
	v_xor_b32_e32 v163, 64, v0
	v_xor_b32_e32 v141, 0x60, v0
	s_lshl_b32 s37, s40, 15
	v_add_u32_e32 v125, s37, v156
	s_add_i32 s46, s37, s31
	s_lshl_b32 s37, s41, 15
	s_add_i32 s37, s37, s31
	s_addk_i32 s37, 0x4000
	ds_read_b128 v[232:235], v0
	ds_read_b128 v[236:239], v162
	ds_read_b128 v[240:243], v163
	ds_read_b128 v[244:247], v141
	ds_read_b64_tr_b16 v[248:249], v125 offset:16384
	ds_read_b64_tr_b16 v[250:251], v125 offset:16896
	ds_read_b64_tr_b16 v[158:159], v125 offset:17408
	ds_read_b64_tr_b16 v[160:161], v125 offset:17920
	ds_read_b64_tr_b16 v[166:167], v125 offset:18432
	ds_read_b64_tr_b16 v[168:169], v125 offset:18944
	v_cvt_pk_bf16_f32 v216, v66, v67
	v_cvt_pk_bf16_f32 v217, v68, v69
	v_cvt_pk_bf16_f32 v218, v70, v71
	v_cvt_pk_bf16_f32 v219, v72, v73
	v_cvt_pk_bf16_f32 v220, v74, v75
	v_cvt_pk_bf16_f32 v221, v76, v77
	v_cvt_pk_bf16_f32 v222, v78, v79
	v_cvt_pk_bf16_f32 v223, v80, v81
	v_add_f32_e32 v121, v121, v252
	v_add_f32_e32 v121, v121, v253
	s_waitcnt lgkmcnt(9)
	v_mfma_f32_32x32x16_bf16 v[66:81], v[232:235], v[110:113], 0
	ds_read_b128 v[232:235], v0 offset:4096
	v_cvt_pk_bf16_f32 v224, v82, v83
	v_cvt_pk_bf16_f32 v225, v84, v85
	v_cvt_pk_bf16_f32 v226, v86, v87
	v_cvt_pk_bf16_f32 v227, v88, v89
	s_waitcnt lgkmcnt(9)
	v_mfma_f32_32x32x16_bf16 v[66:81], v[236:239], v[106:109], v[66:81]
	ds_read_b128 v[236:239], v162 offset:4096
	v_cvt_pk_bf16_f32 v228, v90, v91
	v_cvt_pk_bf16_f32 v229, v92, v93
	v_cvt_pk_bf16_f32 v230, v94, v95
	v_cvt_pk_bf16_f32 v231, v96, v97
	s_waitcnt lgkmcnt(9)
	v_mfma_f32_32x32x16_bf16 v[66:81], v[240:243], v[102:105], v[66:81]
	ds_read_b128 v[240:243], v163 offset:4096
	s_cmp_lg_u32 s99, 0
	s_cbranch_scc0 .Latt_m_nok
	s_mov_b32 m0, s46
	s_nop 0
	global_load_lds_dwordx4 v140, s[100:101]
	s_add_i32 m0, s46, 0x1f80
	s_nop 0
	global_load_lds_dwordx4 v140, s[100:101] offset:128
; #define ATT_LAS __attribute__((address_space(3)))
; __device__ __forceinline__ unsigned cvtpk_s(float lo, float hi) { f32x2_t v = {lo, hi}; bf16x2_t b = __builtin_convertvector(v, bf16x2_t); return __builtin_bit_cast(unsigned, b); }
; #define ATT_SBAR() __builtin_amdgcn_sched_barrier(0)
; #define ATT_VLOAD(dst, d0) do { _Pragma("unroll") for (int ks = 0; ks < 4; ++ks) { dst[2 * ks] = vtr(vp + (d0) * 4096 + ks * 1024); dst[2 * ks + 1] = vtr(vp + (d0) * 4096 + ks * 1024 + 512); } } while (0)
; __device__ __forceinline__ void attn_unit(const int b, const int h, const int qb, const bf16_t* Q, const bf16_t* K, const bf16_t* V, bf16_t* O, ATT_LAS char* shm, const float lam) {
;     ...
;             bf16x8 kf[8]; s16x4 va[8], vb[8];
; #pragma unroll
;             for (int d0 = 0; d0 < 4; ++d0) { kf[2 * d0] = *(const ATT_LAS bf16x8*)(kp + d0 * 2048); kf[2 * d0 + 1] = *(const ATT_LAS bf16x8*)(kp + d0 * 2048 + 512); }
;             ATT_VLOAD(va, 0);
;             ATT_SBAR();
;             f32x16 p0 = f32x16{}, p1 = f32x16{};
; #pragma unroll
;             for (int d0 = 0; d0 < 4; ++d0) { p0 = __builtin_amdgcn_mfma_f32_32x32x16_bf16(kf[2 * d0], qr[d0], p0, 0, 0, 0); p1 = __builtin_amdgcn_mfma_f32_32x32x16_bf16(kf[2 * d0 + 1], qr[d0], p1, 0, 0, 0); }
;             ATT_SBAR();
;             ATT_VLOAD(vb, 1);
;             ATT_SBAR();
; #pragma unroll
;             for (int r = 0; r < 16; ++r) { p0[r] = __builtin_amdgcn_exp2f(p0[r]); p1[r] = __builtin_amdgcn_exp2f(p1[r]); }
;             u32x4 pw[4];
; #pragma unroll
;             for (int j = 0; j < 4; ++j) { pw[0][j] = cvtpk_s(p0[2 * j], p0[2 * j + 1]); pw[1][j] = cvtpk_s(p0[8 + 2 * j], p0[9 + 2 * j]); pw[2][j] = cvtpk_s(p1[2 * j], p1[2 * j + 1]); pw[3][j] = cvtpk_s(p1[8 + 2 * j], p1[9 + 2 * j]); }
;             { float sa = 0.f, sb = 0.f;
; #pragma unroll
;               for (int r = 0; r < 16; ++r) { sa += p0[r]; sb += p1[r]; }
;               l_reg += sa + sb; }
;             ATT_PV(o[0], va);
;             ATT_SBAR();
;             ATT_VLOAD(va, 2);
;             ATT_SBAR();
;             ATT_PV(o[1], vb);
;             ATT_SBAR();
;             ATT_VLOAD(vb, 3);
;             ATT_SBAR();
;             ATT_PV(o[2], va);
;             ATT_SBAR();
;             ATT_PV(o[3], vb);
;     ...
;         }
;         slot = (slot == NSLOT - 1) ? 0 : slot + 1; slot2 = (slot2 == NSLOT - 1) ? 0 : slot2 + 1;
.Latt_m_nok:
	s_waitcnt lgkmcnt(9)
	v_mfma_f32_32x32x16_bf16 v[66:81], v[244:247], v[98:101], v[66:81]
	ds_read_b128 v[244:247], v141 offset:4096
	s_waitcnt lgkmcnt(3)
	v_mfma_f32_32x32x16_bf16 v[82:97], v[232:235], v[110:113], 0
	ds_read_b64_tr_b16 v[232:233], v125 offset:19456
	ds_read_b64_tr_b16 v[234:235], v125 offset:19968
	s_mov_b32 m0, s37
	s_nop 0
	global_load_lds_dwordx4 v142, s[100:101]
	s_waitcnt lgkmcnt(4)
	v_mfma_f32_32x32x16_bf16 v[82:97], v[236:239], v[106:109], v[82:97]
	ds_read_b64_tr_b16 v[236:237], v125 offset:20480
	ds_read_b64_tr_b16 v[238:239], v125 offset:20992
	s_add_i32 m0, s37, 0x1f80
	s_nop 0
	global_load_lds_dwordx4 v142, s[100:101] offset:128
	s_waitcnt lgkmcnt(5)
	v_mfma_f32_32x32x16_bf16 v[82:97], v[240:243], v[102:105], v[82:97]
	ds_read_b64_tr_b16 v[240:241], v125 offset:21504
	ds_read_b64_tr_b16 v[242:243], v125 offset:22016
	s_waitcnt lgkmcnt(6)
	v_mfma_f32_32x32x16_bf16 v[82:97], v[244:247], v[98:101], v[82:97]
	ds_read_b64_tr_b16 v[244:245], v125 offset:22528
	ds_read_b64_tr_b16 v[246:247], v125 offset:23040
	v_mfma_f32_32x32x16_bf16 v[50:65], v[216:219], v[248:251], v[50:65]
	ds_read_b64_tr_b16 v[248:249], v125 offset:23552
	ds_read_b64_tr_b16 v[250:251], v125 offset:24064
	v_exp_f32_e32 v66, v66
	v_exp_f32_e32 v67, v67
	v_mfma_f32_32x32x16_bf16 v[50:65], v[220:223], v[158:161], v[50:65]
	ds_read_b64_tr_b16 v[158:159], v125 offset:24576
	ds_read_b64_tr_b16 v[160:161], v125 offset:25088
	v_add_f32_e32 v252, v66, v67
	v_exp_f32_e32 v68, v68
	v_exp_f32_e32 v69, v69
	v_mfma_f32_32x32x16_bf16 v[50:65], v[224:227], v[166:169], v[50:65]
	ds_read_b64_tr_b16 v[166:167], v125 offset:25600
	ds_read_b64_tr_b16 v[168:169], v125 offset:26112
	v_add_f32_e32 v252, v252, v68
	v_add_f32_e32 v252, v252, v69
	v_exp_f32_e32 v70, v70
	v_exp_f32_e32 v71, v71
	s_waitcnt lgkmcnt(12)
	v_mfma_f32_32x32x16_bf16 v[50:65], v[228:231], v[232:235], v[50:65]
	ds_read_b64_tr_b16 v[232:233], v125 offset:26624
	ds_read_b64_tr_b16 v[234:235], v125 offset:27136
	v_add_f32_e32 v252, v252, v70
	v_add_f32_e32 v252, v252, v71
	v_exp_f32_e32 v72, v72
	v_exp_f32_e32 v73, v73
	s_waitcnt lgkmcnt(12)
	v_mfma_f32_32x32x16_bf16 v[34:49], v[216:219], v[236:239], v[34:49]
	ds_read_b64_tr_b16 v[236:237], v125 offset:27648
	ds_read_b64_tr_b16 v[238:239], v125 offset:28160
	v_add_f32_e32 v252, v252, v72
	v_add_f32_e32 v252, v252, v73
	v_exp_f32_e32 v74, v74
	v_exp_f32_e32 v75, v75
	s_waitcnt lgkmcnt(12)
	v_mfma_f32_32x32x16_bf16 v[34:49], v[220:223], v[240:243], v[34:49]
	ds_read_b64_tr_b16 v[240:241], v125 offset:28672
	ds_read_b64_tr_b16 v[242:243], v125 offset:29184
	v_add_f32_e32 v252, v252, v74
	v_add_f32_e32 v252, v252, v75
	v_exp_f32_e32 v76, v76
	v_exp_f32_e32 v77, v77
	s_waitcnt lgkmcnt(12)
	v_mfma_f32_32x32x16_bf16 v[34:49], v[224:227], v[244:247], v[34:49]
	ds_read_b64_tr_b16 v[244:245], v125 offset:29696
	ds_read_b64_tr_b16 v[246:247], v125 offset:30208
	v_add_f32_e32 v252, v252, v76
	v_add_f32_e32 v252, v252, v77
	v_exp_f32_e32 v78, v78
	v_exp_f32_e32 v79, v79
	s_waitcnt lgkmcnt(12)
	v_mfma_f32_32x32x16_bf16 v[34:49], v[228:231], v[248:251], v[34:49]
	ds_read_b64_tr_b16 v[248:249], v125 offset:30720
	ds_read_b64_tr_b16 v[250:251], v125 offset:31232
	v_add_f32_e32 v252, v252, v78
	v_add_f32_e32 v252, v252, v79
	v_exp_f32_e32 v80, v80
	v_exp_f32_e32 v81, v81
	s_waitcnt lgkmcnt(12)
	v_mfma_f32_32x32x16_bf16 v[18:33], v[216:219], v[158:161], v[18:33]
	ds_read_b64_tr_b16 v[158:159], v125 offset:31744
	ds_read_b64_tr_b16 v[160:161], v125 offset:32256
	v_add_f32_e32 v252, v252, v80
	v_add_f32_e32 v252, v252, v81
	v_exp_f32_e32 v82, v82
	v_exp_f32_e32 v83, v83
	s_waitcnt lgkmcnt(12)
	v_mfma_f32_32x32x16_bf16 v[18:33], v[220:223], v[166:169], v[18:33]
	v_add_f32_e32 v253, v82, v83
	v_exp_f32_e32 v84, v84
	v_exp_f32_e32 v85, v85
	s_waitcnt lgkmcnt(10)
	v_mfma_f32_32x32x16_bf16 v[18:33], v[224:227], v[232:235], v[18:33]
	v_add_f32_e32 v253, v253, v84
	v_add_f32_e32 v253, v253, v85
	v_exp_f32_e32 v86, v86
	v_exp_f32_e32 v87, v87
	s_waitcnt lgkmcnt(8)
	v_mfma_f32_32x32x16_bf16 v[18:33], v[228:231], v[236:239], v[18:33]
	v_add_f32_e32 v253, v253, v86
	v_add_f32_e32 v253, v253, v87
	v_exp_f32_e32 v88, v88
	v_exp_f32_e32 v89, v89
	s_waitcnt lgkmcnt(6)
	v_mfma_f32_32x32x16_bf16 v[2:17], v[216:219], v[240:243], v[2:17]
	v_add_f32_e32 v253, v253, v88
	v_add_f32_e32 v253, v253, v89
	v_exp_f32_e32 v90, v90
	v_exp_f32_e32 v91, v91
	s_waitcnt lgkmcnt(4)
	v_mfma_f32_32x32x16_bf16 v[2:17], v[220:223], v[244:247], v[2:17]
	v_add_f32_e32 v253, v253, v90
	v_add_f32_e32 v253, v253, v91
	v_exp_f32_e32 v92, v92
	v_exp_f32_e32 v93, v93
	s_waitcnt lgkmcnt(2)
	v_mfma_f32_32x32x16_bf16 v[2:17], v[224:227], v[248:251], v[2:17]
	v_add_f32_e32 v253, v253, v92
	v_add_f32_e32 v253, v253, v93
	v_exp_f32_e32 v94, v94
	v_exp_f32_e32 v95, v95
	s_waitcnt lgkmcnt(0)
	v_mfma_f32_32x32x16_bf16 v[2:17], v[228:231], v[158:161], v[2:17]
	v_add_f32_e32 v253, v253, v94
	v_add_f32_e32 v253, v253, v95
	v_exp_f32_e32 v96, v96
	v_exp_f32_e32 v97, v97
	v_add_f32_e32 v253, v253, v96
	v_add_f32_e32 v253, v253, v97
	s_add_i32 s16, s16, 1
	s_add_i32 s36, s40, 1
	s_cmp_lg_u32 s40, 2
	s_cselect_b32 s40, s36, 0
	s_add_i32 s36, s41, 1
	s_cmp_lg_u32 s41, 2
	s_cselect_b32 s41, s36, 0
	s_add_u32 s100, s100, 0x10000
	s_addc_u32 s101, s101, 0
	s_cmp_lt_u32 s16, s44
	s_cbranch_scc1 .Latt_top
; #define ATT_LAS __attribute__((address_space(3)))
; __device__ __forceinline__ unsigned cvtpk_s(float lo, float hi) { f32x2_t v = {lo, hi}; bf16x2_t b = __builtin_convertvector(v, bf16x2_t); return __builtin_bit_cast(unsigned, b); }
; #define ATT_WAIT_BAR(N) asm volatile("s_waitcnt vmcnt(" #N ") lgkmcnt(0)\n\ts_barrier" ::: "memory")
; #define ATT_SBAR() __builtin_amdgcn_sched_barrier(0)
; __device__ __forceinline__ void attn_unit(const int b, const int h, const int qb, const bf16_t* Q, const bf16_t* K, const bf16_t* V, bf16_t* O, ATT_LAS char* shm, const float lam) {
;     ...
;         if (t + 1 < NT) { ATT_WAIT_BAR(4); } else { ATT_WAIT_BAR(0); }
;         if (t + 2 < NT) DMA_T(t + 2, slot2);
;         if (t <= mylast) {
;             const lds_cptr kp = kp0 + slot * SLOTB; const lds_cptr vp = vp0 + slot * SLOTB;
;     ...
;             bf16x8 kf[8]; s16x4 va[8], vb[8];
; #pragma unroll
;             for (int d0 = 0; d0 < 4; ++d0) { kf[2 * d0] = *(const ATT_LAS bf16x8*)(kp + d0 * 2048); kf[2 * d0 + 1] = *(const ATT_LAS bf16x8*)(kp + d0 * 2048 + 512); }
;             ATT_VLOAD(va, 0);
;             ATT_SBAR();
;             f32x16 p0 = f32x16{}, p1 = f32x16{};
; #pragma unroll
;             for (int d0 = 0; d0 < 4; ++d0) { p0 = __builtin_amdgcn_mfma_f32_32x32x16_bf16(kf[2 * d0], qr[d0], p0, 0, 0, 0); p1 = __builtin_amdgcn_mfma_f32_32x32x16_bf16(kf[2 * d0 + 1], qr[d0], p1, 0, 0, 0); }
;             ATT_SBAR();
;             ATT_VLOAD(vb, 1);
;             ATT_SBAR();
; #pragma unroll
;             for (int r = 0; r < 16; ++r) { p0[r] = __builtin_amdgcn_exp2f(p0[r]); p1[r] = __builtin_amdgcn_exp2f(p1[r]); }
;             u32x4 pw[4];
; #pragma unroll
;             for (int j = 0; j < 4; ++j) { pw[0][j] = cvtpk_s(p0[2 * j], p0[2 * j + 1]); pw[1][j] = cvtpk_s(p0[8 + 2 * j], p0[9 + 2 * j]); pw[2][j] = cvtpk_s(p1[2 * j], p1[2 * j + 1]); pw[3][j] = cvtpk_s(p1[8 + 2 * j], p1[9 + 2 * j]); }
;             { float sa = 0.f, sb = 0.f;
; #pragma unroll
;               for (int r = 0; r < 16; ++r) { sa += p0[r]; sb += p1[r]; }
;               l_reg += sa + sb; }
;             ATT_PV(o[0], va);
;             ATT_SBAR();
;             ATT_VLOAD(va, 2);
;             ATT_SBAR();
;             ATT_PV(o[1], vb);
;             ATT_SBAR();
;             ATT_VLOAD(vb, 3);
;             ATT_SBAR();
;             ATT_PV(o[2], va);
;             ATT_SBAR();
;             ATT_PV(o[3], vb);
.Latt_tail:
	s_waitcnt vmcnt(2)
	s_barrier
	s_cmp_lg_u32 s98, 0
	s_cbranch_scc0 .Latt_low
	s_add_i32 s36, s40, 1
	s_cmp_lg_u32 s40, 2
	s_cselect_b32 s36, s36, 0
	s_lshl_b32 s36, s36, 15
	v_add_u32_e32 v0, s36, v123
	v_xor_b32_e32 v162, 32, v0
	v_xor_b32_e32 v163, 64, v0
	v_xor_b32_e32 v141, 0x60, v0
	s_lshl_b32 s37, s40, 15
	v_add_u32_e32 v125, s37, v156
	ds_read_b128 v[232:235], v0
	ds_read_b128 v[236:239], v162
	ds_read_b128 v[240:243], v163
	ds_read_b128 v[244:247], v141
	ds_read_b64_tr_b16 v[248:249], v125 offset:16384
	ds_read_b64_tr_b16 v[250:251], v125 offset:16896
	ds_read_b64_tr_b16 v[158:159], v125 offset:17408
	ds_read_b64_tr_b16 v[160:161], v125 offset:17920
	ds_read_b64_tr_b16 v[166:167], v125 offset:18432
	ds_read_b64_tr_b16 v[168:169], v125 offset:18944
	v_cvt_pk_bf16_f32 v216, v66, v67
	v_cvt_pk_bf16_f32 v217, v68, v69
	v_cvt_pk_bf16_f32 v218, v70, v71
	v_cvt_pk_bf16_f32 v219, v72, v73
	v_cvt_pk_bf16_f32 v220, v74, v75
	v_cvt_pk_bf16_f32 v221, v76, v77
	v_cvt_pk_bf16_f32 v222, v78, v79
	v_cvt_pk_bf16_f32 v223, v80, v81
	v_add_f32_e32 v121, v121, v252
	v_add_f32_e32 v121, v121, v253
	s_waitcnt lgkmcnt(9)
	v_mfma_f32_32x32x16_bf16 v[66:81], v[232:235], v[110:113], 0
	ds_read_b128 v[232:235], v0 offset:4096
	v_cvt_pk_bf16_f32 v224, v82, v83
	v_cvt_pk_bf16_f32 v225, v84, v85
	v_cvt_pk_bf16_f32 v226, v86, v87
	v_cvt_pk_bf16_f32 v227, v88, v89
	s_waitcnt lgkmcnt(9)
	v_mfma_f32_32x32x16_bf16 v[66:81], v[236:239], v[106:109], v[66:81]
	ds_read_b128 v[236:239], v162 offset:4096
	v_cvt_pk_bf16_f32 v228, v90, v91
	v_cvt_pk_bf16_f32 v229, v92, v93
	v_cvt_pk_bf16_f32 v230, v94, v95
	v_cvt_pk_bf16_f32 v231, v96, v97
	s_waitcnt lgkmcnt(9)
	v_mfma_f32_32x32x16_bf16 v[66:81], v[240:243], v[102:105], v[66:81]
	ds_read_b128 v[240:243], v163 offset:4096
	s_waitcnt lgkmcnt(9)
	v_mfma_f32_32x32x16_bf16 v[66:81], v[244:247], v[98:101], v[66:81]
	ds_read_b128 v[244:247], v141 offset:4096
	s_waitcnt lgkmcnt(3)
	v_mfma_f32_32x32x16_bf16 v[82:97], v[232:235], v[110:113], 0
	ds_read_b64_tr_b16 v[232:233], v125 offset:19456
	ds_read_b64_tr_b16 v[234:235], v125 offset:19968
	s_waitcnt lgkmcnt(4)
	v_mfma_f32_32x32x16_bf16 v[82:97], v[236:239], v[106:109], v[82:97]
	ds_read_b64_tr_b16 v[236:237], v125 offset:20480
	ds_read_b64_tr_b16 v[238:239], v125 offset:20992
	s_waitcnt lgkmcnt(5)
	v_mfma_f32_32x32x16_bf16 v[82:97], v[240:243], v[102:105], v[82:97]
	ds_read_b64_tr_b16 v[240:241], v125 offset:21504
	ds_read_b64_tr_b16 v[242:243], v125 offset:22016
	s_waitcnt lgkmcnt(6)
	v_mfma_f32_32x32x16_bf16 v[82:97], v[244:247], v[98:101], v[82:97]
	ds_read_b64_tr_b16 v[244:245], v125 offset:22528
	ds_read_b64_tr_b16 v[246:247], v125 offset:23040
	v_mfma_f32_32x32x16_bf16 v[50:65], v[216:219], v[248:251], v[50:65]
	ds_read_b64_tr_b16 v[248:249], v125 offset:23552
	ds_read_b64_tr_b16 v[250:251], v125 offset:24064
	v_exp_f32_e32 v66, v66
	v_exp_f32_e32 v67, v67
	v_mfma_f32_32x32x16_bf16 v[50:65], v[220:223], v[158:161], v[50:65]
	ds_read_b64_tr_b16 v[158:159], v125 offset:24576
	ds_read_b64_tr_b16 v[160:161], v125 offset:25088
	v_add_f32_e32 v252, v66, v67
	v_exp_f32_e32 v68, v68
	v_exp_f32_e32 v69, v69
	v_mfma_f32_32x32x16_bf16 v[50:65], v[224:227], v[166:169], v[50:65]
	ds_read_b64_tr_b16 v[166:167], v125 offset:25600
	ds_read_b64_tr_b16 v[168:169], v125 offset:26112
	v_add_f32_e32 v252, v252, v68
	v_add_f32_e32 v252, v252, v69
	v_exp_f32_e32 v70, v70
	v_exp_f32_e32 v71, v71
	s_waitcnt lgkmcnt(12)
	v_mfma_f32_32x32x16_bf16 v[50:65], v[228:231], v[232:235], v[50:65]
	ds_read_b64_tr_b16 v[232:233], v125 offset:26624
	ds_read_b64_tr_b16 v[234:235], v125 offset:27136
	v_add_f32_e32 v252, v252, v70
	v_add_f32_e32 v252, v252, v71
	v_exp_f32_e32 v72, v72
	v_exp_f32_e32 v73, v73
	s_waitcnt lgkmcnt(12)
	v_mfma_f32_32x32x16_bf16 v[34:49], v[216:219], v[236:239], v[34:49]
	ds_read_b64_tr_b16 v[236:237], v125 offset:27648
	ds_read_b64_tr_b16 v[238:239], v125 offset:28160
	v_add_f32_e32 v252, v252, v72
	v_add_f32_e32 v252, v252, v73
	v_exp_f32_e32 v74, v74
	v_exp_f32_e32 v75, v75
	s_waitcnt lgkmcnt(12)
	v_mfma_f32_32x32x16_bf16 v[34:49], v[220:223], v[240:243], v[34:49]
	ds_read_b64_tr_b16 v[240:241], v125 offset:28672
	ds_read_b64_tr_b16 v[242:243], v125 offset:29184
	v_add_f32_e32 v252, v252, v74
	v_add_f32_e32 v252, v252, v75
	v_exp_f32_e32 v76, v76
	v_exp_f32_e32 v77, v77
	s_waitcnt lgkmcnt(12)
	v_mfma_f32_32x32x16_bf16 v[34:49], v[224:227], v[244:247], v[34:49]
	ds_read_b64_tr_b16 v[244:245], v125 offset:29696
	ds_read_b64_tr_b16 v[246:247], v125 offset:30208
	v_add_f32_e32 v252, v252, v76
	v_add_f32_e32 v252, v252, v77
	v_exp_f32_e32 v78, v78
	v_exp_f32_e32 v79, v79
	s_waitcnt lgkmcnt(12)
	v_mfma_f32_32x32x16_bf16 v[34:49], v[228:231], v[248:251], v[34:49]
	ds_read_b64_tr_b16 v[248:249], v125 offset:30720
	ds_read_b64_tr_b16 v[250:251], v125 offset:31232
	v_add_f32_e32 v252, v252, v78
	v_add_f32_e32 v252, v252, v79
	v_exp_f32_e32 v80, v80
	v_exp_f32_e32 v81, v81
	s_waitcnt lgkmcnt(12)
	v_mfma_f32_32x32x16_bf16 v[18:33], v[216:219], v[158:161], v[18:33]
	ds_read_b64_tr_b16 v[158:159], v125 offset:31744
	ds_read_b64_tr_b16 v[160:161], v125 offset:32256
	v_add_f32_e32 v252, v252, v80
	v_add_f32_e32 v252, v252, v81
	v_exp_f32_e32 v82, v82
	v_exp_f32_e32 v83, v83
	s_waitcnt lgkmcnt(12)
	v_mfma_f32_32x32x16_bf16 v[18:33], v[220:223], v[166:169], v[18:33]
	v_add_f32_e32 v253, v82, v83
	v_exp_f32_e32 v84, v84
	v_exp_f32_e32 v85, v85
	s_waitcnt lgkmcnt(10)
	v_mfma_f32_32x32x16_bf16 v[18:33], v[224:227], v[232:235], v[18:33]
	v_add_f32_e32 v253, v253, v84
	v_add_f32_e32 v253, v253, v85
	v_exp_f32_e32 v86, v86
	v_exp_f32_e32 v87, v87
	s_waitcnt lgkmcnt(8)
	v_mfma_f32_32x32x16_bf16 v[18:33], v[228:231], v[236:239], v[18:33]
	v_add_f32_e32 v253, v253, v86
	v_add_f32_e32 v253, v253, v87
	v_exp_f32_e32 v88, v88
	v_exp_f32_e32 v89, v89
	s_waitcnt lgkmcnt(6)
	v_mfma_f32_32x32x16_bf16 v[2:17], v[216:219], v[240:243], v[2:17]
	v_add_f32_e32 v253, v253, v88
	v_add_f32_e32 v253, v253, v89
	v_exp_f32_e32 v90, v90
	v_exp_f32_e32 v91, v91
	s_waitcnt lgkmcnt(4)
	v_mfma_f32_32x32x16_bf16 v[2:17], v[220:223], v[244:247], v[2:17]
	v_add_f32_e32 v253, v253, v90
	v_add_f32_e32 v253, v253, v91
	v_exp_f32_e32 v92, v92
	v_exp_f32_e32 v93, v93
	s_waitcnt lgkmcnt(2)
	v_mfma_f32_32x32x16_bf16 v[2:17], v[224:227], v[248:251], v[2:17]
	v_add_f32_e32 v253, v253, v92
	v_add_f32_e32 v253, v253, v93
	v_exp_f32_e32 v94, v94
	v_exp_f32_e32 v95, v95
	s_waitcnt lgkmcnt(0)
	v_mfma_f32_32x32x16_bf16 v[2:17], v[228:231], v[158:161], v[2:17]
	v_add_f32_e32 v253, v253, v94
	v_add_f32_e32 v253, v253, v95
	v_exp_f32_e32 v96, v96
	v_exp_f32_e32 v97, v97
	v_add_f32_e32 v253, v253, v96
	v_add_f32_e32 v253, v253, v97
	s_add_i32 s16, s16, 1
	s_add_i32 s36, s40, 1
	s_cmp_lg_u32 s40, 2
	s_cselect_b32 s40, s36, 0
	s_waitcnt vmcnt(0)
	s_barrier
; #define ATT_SBAR() __builtin_amdgcn_sched_barrier(0)
; #define ATT_VLOAD(dst, d0) do { _Pragma("unroll") for (int ks = 0; ks < 4; ++ks) { dst[2 * ks] = vtr(vp + (d0) * 4096 + ks * 1024); dst[2 * ks + 1] = vtr(vp + (d0) * 4096 + ks * 1024 + 512); } } while (0)
; #define ATT_PV(acc, src) do { _Pragma("unroll") for (int ks = 0; ks < 4; ++ks) { const bf16x8 vf_ = (bf16x8){src[2 * ks][0], src[2 * ks][1], src[2 * ks][2], src[2 * ks][3], src[2 * ks + 1][0], src[2 * ks + 1][1], src[2 * ks + 1][2], src[2 * ks + 1][3]}; \
;                 acc = __builtin_amdgcn_mfma_f32_32x32x16_bf16(__builtin_bit_cast(bf16x8, pw[ks]), vf_, acc, 0, 0, 0); } } while (0)
; __device__ __forceinline__ void attn_unit(const int b, const int h, const int qb, const bf16_t* Q, const bf16_t* K, const bf16_t* V, bf16_t* O, ATT_LAS char* shm, const float lam) {
;     ...
;             ATT_PV(o[0], va);
;             ATT_SBAR();
;             ATT_VLOAD(va, 2);
;             ATT_SBAR();
;             ATT_PV(o[1], vb);
;             ATT_SBAR();
;             ATT_VLOAD(vb, 3);
;             ATT_SBAR();
;             ATT_PV(o[2], va);
;             ATT_SBAR();
;             ATT_PV(o[3], vb);
	s_lshl_b32 s37, s40, 15
	v_add_u32_e32 v125, s37, v156
	ds_read_b64_tr_b16 v[248:249], v125 offset:16384
	ds_read_b64_tr_b16 v[250:251], v125 offset:16896
	ds_read_b64_tr_b16 v[158:159], v125 offset:17408
	ds_read_b64_tr_b16 v[160:161], v125 offset:17920
	ds_read_b64_tr_b16 v[166:167], v125 offset:18432
	ds_read_b64_tr_b16 v[168:169], v125 offset:18944
	ds_read_b64_tr_b16 v[232:233], v125 offset:19456
	ds_read_b64_tr_b16 v[234:235], v125 offset:19968
	ds_read_b64_tr_b16 v[236:237], v125 offset:20480
	ds_read_b64_tr_b16 v[238:239], v125 offset:20992
	ds_read_b64_tr_b16 v[240:241], v125 offset:21504
	ds_read_b64_tr_b16 v[242:243], v125 offset:22016
	ds_read_b64_tr_b16 v[244:245], v125 offset:22528
	ds_read_b64_tr_b16 v[246:247], v125 offset:23040
	v_cvt_pk_bf16_f32 v216, v66, v67
	v_cvt_pk_bf16_f32 v217, v68, v69
	v_cvt_pk_bf16_f32 v218, v70, v71
	v_cvt_pk_bf16_f32 v219, v72, v73
	v_cvt_pk_bf16_f32 v220, v74, v75
	v_cvt_pk_bf16_f32 v221, v76, v77
	v_cvt_pk_bf16_f32 v222, v78, v79
	v_cvt_pk_bf16_f32 v223, v80, v81
	v_cvt_pk_bf16_f32 v224, v82, v83
	v_cvt_pk_bf16_f32 v225, v84, v85
	v_cvt_pk_bf16_f32 v226, v86, v87
	v_cvt_pk_bf16_f32 v227, v88, v89
	v_cvt_pk_bf16_f32 v228, v90, v91
	v_cvt_pk_bf16_f32 v229, v92, v93
	v_cvt_pk_bf16_f32 v230, v94, v95
	v_cvt_pk_bf16_f32 v231, v96, v97
	v_add_f32_e32 v121, v121, v252
	v_add_f32_e32 v121, v121, v253
	s_waitcnt lgkmcnt(12)
	v_mfma_f32_32x32x16_bf16 v[50:65], v[216:219], v[248:251], v[50:65]
	ds_read_b64_tr_b16 v[248:249], v125 offset:23552
	ds_read_b64_tr_b16 v[250:251], v125 offset:24064
	s_waitcnt lgkmcnt(12)
	v_mfma_f32_32x32x16_bf16 v[50:65], v[220:223], v[158:161], v[50:65]
	ds_read_b64_tr_b16 v[158:159], v125 offset:24576
	ds_read_b64_tr_b16 v[160:161], v125 offset:25088
	s_waitcnt lgkmcnt(12)
	v_mfma_f32_32x32x16_bf16 v[50:65], v[224:227], v[166:169], v[50:65]
	ds_read_b64_tr_b16 v[166:167], v125 offset:25600
	ds_read_b64_tr_b16 v[168:169], v125 offset:26112
	s_waitcnt lgkmcnt(12)
	v_mfma_f32_32x32x16_bf16 v[50:65], v[228:231], v[232:235], v[50:65]
	ds_read_b64_tr_b16 v[232:233], v125 offset:26624
	ds_read_b64_tr_b16 v[234:235], v125 offset:27136
	s_waitcnt lgkmcnt(12)
	v_mfma_f32_32x32x16_bf16 v[34:49], v[216:219], v[236:239], v[34:49]
	ds_read_b64_tr_b16 v[236:237], v125 offset:27648
	ds_read_b64_tr_b16 v[238:239], v125 offset:28160
	s_waitcnt lgkmcnt(12)
	v_mfma_f32_32x32x16_bf16 v[34:49], v[220:223], v[240:243], v[34:49]
	ds_read_b64_tr_b16 v[240:241], v125 offset:28672
	ds_read_b64_tr_b16 v[242:243], v125 offset:29184
	s_waitcnt lgkmcnt(12)
	v_mfma_f32_32x32x16_bf16 v[34:49], v[224:227], v[244:247], v[34:49]
	ds_read_b64_tr_b16 v[244:245], v125 offset:29696
	ds_read_b64_tr_b16 v[246:247], v125 offset:30208
	s_waitcnt lgkmcnt(12)
	v_mfma_f32_32x32x16_bf16 v[34:49], v[228:231], v[248:251], v[34:49]
	ds_read_b64_tr_b16 v[248:249], v125 offset:30720
	ds_read_b64_tr_b16 v[250:251], v125 offset:31232
	s_waitcnt lgkmcnt(12)
	v_mfma_f32_32x32x16_bf16 v[18:33], v[216:219], v[158:161], v[18:33]
	ds_read_b64_tr_b16 v[158:159], v125 offset:31744
	ds_read_b64_tr_b16 v[160:161], v125 offset:32256
	s_waitcnt lgkmcnt(12)
	v_mfma_f32_32x32x16_bf16 v[18:33], v[220:223], v[166:169], v[18:33]
	s_waitcnt lgkmcnt(10)
	v_mfma_f32_32x32x16_bf16 v[18:33], v[224:227], v[232:235], v[18:33]
	s_waitcnt lgkmcnt(8)
	v_mfma_f32_32x32x16_bf16 v[18:33], v[228:231], v[236:239], v[18:33]
	s_waitcnt lgkmcnt(6)
	v_mfma_f32_32x32x16_bf16 v[2:17], v[216:219], v[240:243], v[2:17]
	s_waitcnt lgkmcnt(4)
	v_mfma_f32_32x32x16_bf16 v[2:17], v[220:223], v[244:247], v[2:17]
	s_waitcnt lgkmcnt(2)
	v_mfma_f32_32x32x16_bf16 v[2:17], v[224:227], v[248:251], v[2:17]
	s_waitcnt lgkmcnt(0)
	v_mfma_f32_32x32x16_bf16 v[2:17], v[228:231], v[158:161], v[2:17]
	s_branch .LBB0_474
